# v62 + the 6 MLA LDS-DMA pieces issued spread through the softmax VALU section (one per ~19 VALU) instead of back-to-back after the barrier
# baseline (speedup 1.0000x reference)
; #define LAS __attribute__((address_space(3)))
; template <int MODE, int NQ> ...
;     ...
;     while (j >= 0) {
;         const int bsel = it & 1;
;         stage_store<HASP, HASV>(st, lds + OFF_K + bsel * KBUF, lds + OFF_V + bsel * VBUF, tid);
;         __syncthreads();
;         int jn;
;         if (MODE == M_SEL) { jn = rem ? (int)__builtin_ctzll(rem) : -1; rem &= rem - 1ull; } else { jn = (j + 1 <= jhi) ? j + 1 : -1; }
;         if (jn >= 0) stage_load<HASP, HASV>(st, Kg + (size_t)jn * 64 * ldk, ldk, Pg + (size_t)jn * 64 * 64, Vg + (size_t)jn * 64 * ldv, ldv, tid);
;         const bool lvw = (MODE == M_SEL) ? (((mymask >> j) & 1ull) != 0ull) : true;
;         if (!((MODE == M_MLA && 64 * j > wmax) || (MODE == M_SEL && !__any(lvw)))) {
;             const LAS unsigned char* kb = kb_l + bsel * KBUF; const LAS unsigned char* vb = vb_l + bsel * VBUF;
;             f32x16 s0, s1;
; #pragma unroll
;             for (int r = 0; r < 16; ++r) { s0[r] = 0.f; s1[r] = 0.f; }
;             {
;                 constexpr int KW = (NQ == 8) ? 6 : ATT_KW12;
;                 bf16x8 kf[KW];
; #pragma unroll
;                 for (int i = 0; i < KW; ++i) kf[i] = *(const LAS bf16x8*)(kb + (i & 1) * 32 * KP + (i >> 1) * 32);
;                 __builtin_amdgcn_sched_barrier(0);
; #pragma unroll
;                 for (int i = 0; i < 2 * NQ; ++i) {
;                     if (i & 1) s1 = __builtin_amdgcn_mfma_f32_32x32x16_bf16(kf[i % KW], qf[i >> 1], s1, 0, 0, 0);
;                     else s0 = __builtin_amdgcn_mfma_f32_32x32x16_bf16(kf[i % KW], qf[i >> 1], s0, 0, 0, 0);
;                     if (i + KW < 2 * NQ) { kf[i % KW] = *(const LAS bf16x8*)(kb + ((i + KW) & 1) * 32 * KP + ((i + KW) >> 1) * 32); __builtin_amdgcn_sched_barrier(0); }
;                 }
;             }
;             const int hl = hiB - 64 * j - 4 * hi, ll = loB - 64 * j - 4 * hi;
;             const bool lv = lvw;
;             bool need = true;
;             if (MODE == M_WIN || MODE == M_MLA || MODE == M_SEL) need = __any(!((hl >= 63) && (ll < 0)));
;             if (need) {
;                 const float NEG = -__builtin_inff();
; #pragma unroll
;                 for (int r = 0; r < 16; ++r) { const int c = (r & 3) + 8 * (r >> 2);
;                     if (!(lv && c <= hl && c > ll)) s0[r] = NEG;
;                     if (!(lv && c + 32 <= hl && c + 32 > ll)) s1[r] = NEG; }
;             }
.LBB0_962:
	s_and_b32 s65, s64, 1
	s_mul_i32 s0, s65, 0x6400
	s_waitcnt vmcnt(0) lgkmcnt(0)
	s_barrier
.LBB0_964:
	s_cmp_gt_i32 s33, s96
	s_cbranch_scc1 .LBB0_970
	v_add_u32_e32 v189, s0, v171
	ds_read_b128 v[66:69], v189
	ds_read_b128 v[192:195], v189 offset:32
	ds_read_b128 v[82:85], v189 offset:12800
	ds_read_b128 v[196:199], v189 offset:12832
	ds_read_b128 v[200:203], v189 offset:64
	ds_read_b128 v[204:207], v189 offset:96
	ds_read_b128 v[208:211], v189 offset:12864
	ds_read_b128 v[212:215], v189 offset:12896
	ds_read_b128 v[216:219], v189 offset:128
	ds_read_b128 v[220:223], v189 offset:160
	ds_read_b128 v[224:227], v189 offset:12928
	ds_read_b128 v[228:231], v189 offset:12960
	s_waitcnt lgkmcnt(11)
	v_mfma_f32_32x32x16_bf16 v[66:81], v[66:69], v[98:101], 0
	ds_read_b128 v[232:235], v189 offset:192
	s_waitcnt lgkmcnt(10)
	v_mfma_f32_32x32x16_bf16 v[82:97], v[82:85], v[98:101], 0
	ds_read_b128 v[236:239], v189 offset:12992
	v_mfma_f32_32x32x16_bf16 v[66:81], v[192:195], v[102:105], v[66:81]
	ds_read_b128 v[240:243], v189 offset:224
	s_waitcnt lgkmcnt(11)
	v_mfma_f32_32x32x16_bf16 v[82:97], v[196:199], v[102:105], v[82:97]
	ds_read_b128 v[192:195], v189 offset:13024
	s_waitcnt lgkmcnt(11)
	v_mfma_f32_32x32x16_bf16 v[66:81], v[200:203], v[106:109], v[66:81]
	ds_read_b128 v[196:199], v189 offset:256
	s_waitcnt lgkmcnt(10)
	v_mfma_f32_32x32x16_bf16 v[82:97], v[208:211], v[106:109], v[82:97]
	ds_read_b128 v[200:203], v189 offset:13056
	v_mfma_f32_32x32x16_bf16 v[66:81], v[204:207], v[110:113], v[66:81]
	ds_read_b128 v[208:211], v189 offset:288
	s_waitcnt lgkmcnt(11)
	v_mfma_f32_32x32x16_bf16 v[82:97], v[212:215], v[110:113], v[82:97]
	ds_read_b128 v[204:207], v189 offset:13088
	s_waitcnt lgkmcnt(11)
	v_mfma_f32_32x32x16_bf16 v[66:81], v[216:219], v[114:117], v[66:81]
	ds_read_b128 v[212:215], v189 offset:320
	s_waitcnt lgkmcnt(10)
	v_mfma_f32_32x32x16_bf16 v[82:97], v[224:227], v[114:117], v[82:97]
	ds_read_b128 v[216:219], v189 offset:13120
	v_mfma_f32_32x32x16_bf16 v[66:81], v[220:223], v[118:121], v[66:81]
	ds_read_b128 v[224:227], v189 offset:352
	s_waitcnt lgkmcnt(11)
	v_mfma_f32_32x32x16_bf16 v[82:97], v[228:231], v[118:121], v[82:97]
	ds_read_b128 v[220:223], v189 offset:13152
	s_waitcnt lgkmcnt(11)
	v_mfma_f32_32x32x16_bf16 v[66:81], v[232:235], v[122:125], v[66:81]
	v_cmp_gt_i32_e32 vcc, 63, v187
	s_waitcnt lgkmcnt(10)
	v_mfma_f32_32x32x16_bf16 v[82:97], v[236:239], v[122:125], v[82:97]
	s_waitcnt lgkmcnt(9)
	v_mfma_f32_32x32x16_bf16 v[66:81], v[240:243], v[126:129], v[66:81]
	s_waitcnt lgkmcnt(8)
	v_mfma_f32_32x32x16_bf16 v[82:97], v[192:195], v[126:129], v[82:97]
	s_waitcnt lgkmcnt(7)
	v_mfma_f32_32x32x16_bf16 v[66:81], v[196:199], v[130:133], v[66:81]
	s_waitcnt lgkmcnt(6)
	v_mfma_f32_32x32x16_bf16 v[82:97], v[200:203], v[130:133], v[82:97]
	s_waitcnt lgkmcnt(5)
	v_mfma_f32_32x32x16_bf16 v[66:81], v[208:211], v[134:137], v[66:81]
	s_waitcnt lgkmcnt(4)
	v_mfma_f32_32x32x16_bf16 v[82:97], v[204:207], v[134:137], v[82:97]
	s_waitcnt lgkmcnt(3)
	v_mfma_f32_32x32x16_bf16 v[66:81], v[212:215], v[138:141], v[66:81]
	s_waitcnt lgkmcnt(2)
	v_mfma_f32_32x32x16_bf16 v[82:97], v[216:219], v[138:141], v[82:97]
	s_waitcnt lgkmcnt(1)
	v_mfma_f32_32x32x16_bf16 v[66:81], v[224:227], v[142:145], v[66:81]
	s_waitcnt lgkmcnt(0)
	v_mfma_f32_32x32x16_bf16 v[82:97], v[220:223], v[142:145], v[82:97]
	s_cbranch_vccz .LBB0_967
	v_cmp_gt_i32_e64 s[60:61], 26, v187
	v_cmp_gt_i32_e64 s[62:63], 27, v187
	v_cmp_gt_i32_e64 s[58:59], 25, v187
	s_and_b64 s[60:61], s[62:63], s[60:61]
	v_cmp_gt_i32_e64 s[56:57], 24, v187
	s_and_b64 s[58:59], s[60:61], s[58:59]
	v_cmp_gt_i32_e64 s[54:55], 19, v187
	s_and_b64 s[56:57], s[58:59], s[56:57]
	v_cmp_gt_i32_e64 s[52:53], 18, v187
	s_and_b64 s[54:55], s[56:57], s[54:55]
	v_cmp_gt_i32_e64 s[50:51], 17, v187
	s_and_b64 s[52:53], s[54:55], s[52:53]
	v_cmp_gt_i32_e64 s[48:49], 16, v187
	s_and_b64 s[50:51], s[52:53], s[50:51]
	v_cmp_gt_i32_e64 s[46:47], 11, v187
	s_and_b64 s[48:49], s[50:51], s[48:49]
	v_cmp_gt_i32_e64 s[44:45], 10, v187
	s_and_b64 s[46:47], s[48:49], s[46:47]
	v_cmp_gt_i32_e64 s[42:43], 9, v187
	s_and_b64 s[44:45], s[46:47], s[44:45]
	v_cmp_gt_i32_e64 s[40:41], 8, v187
	s_and_b64 s[42:43], s[44:45], s[42:43]
	v_cmp_gt_i32_e64 s[38:39], 3, v187
	s_and_b64 s[40:41], s[42:43], s[40:41]
	v_cmp_gt_i32_e64 s[36:37], 2, v187
	s_and_b64 s[38:39], s[40:41], s[38:39]
	v_cmp_gt_i32_e64 s[34:35], 1, v187
	s_and_b64 s[36:37], s[38:39], s[36:37]
	v_cmp_gt_i32_e64 s[28:29], 0, v187
	s_and_b64 s[34:35], s[36:37], s[34:35]
	s_and_b64 s[28:29], s[34:35], s[28:29]
	v_cmp_gt_i32_e64 s[26:27], 58, v187
	v_cndmask_b32_e64 v66, v66, v1, s[28:29]
	v_cmp_gt_i32_e64 s[28:29], 59, v187
	v_cmp_gt_i32_e64 s[24:25], 57, v187
	s_and_b64 s[26:27], s[28:29], s[26:27]
	v_cmp_gt_i32_e64 s[22:23], 56, v187
	s_and_b64 s[24:25], s[26:27], s[24:25]
	v_cmp_gt_i32_e64 s[20:21], 51, v187
	s_and_b64 s[22:23], s[24:25], s[22:23]
	v_cmp_gt_i32_e64 s[18:19], 50, v187
	s_and_b64 s[20:21], s[22:23], s[20:21]
	v_cmp_gt_i32_e64 s[0:1], 49, v187
	s_and_b64 s[18:19], s[20:21], s[18:19]
	v_cmp_gt_i32_e64 s[16:17], 48, v187
	s_and_b64 s[0:1], s[18:19], s[0:1]
	v_cmp_gt_i32_e64 s[14:15], 43, v187
	v_cndmask_b32_e64 v91, v91, v1, s[0:1]
	s_and_b64 s[0:1], s[0:1], s[16:17]
	v_cmp_gt_i32_e64 s[12:13], 42, v187
	v_cndmask_b32_e64 v90, v90, v1, s[0:1]
	s_and_b64 s[0:1], s[0:1], s[14:15]
	v_cmp_gt_i32_e64 s[10:11], 41, v187
	v_cndmask_b32_e64 v89, v89, v1, s[0:1]
	s_and_b64 s[0:1], s[0:1], s[12:13]
	v_cmp_gt_i32_e64 s[8:9], 40, v187
	v_cndmask_b32_e64 v88, v88, v1, s[0:1]
	s_and_b64 s[0:1], s[0:1], s[10:11]
	v_cmp_gt_i32_e64 s[6:7], 35, v187
	v_cndmask_b32_e64 v87, v87, v1, s[0:1]
	s_and_b64 s[0:1], s[0:1], s[8:9]
	v_cmp_gt_i32_e64 s[4:5], 34, v187
	v_cndmask_b32_e64 v86, v86, v1, s[0:1]
	s_and_b64 s[0:1], s[0:1], s[6:7]
	v_cmp_gt_i32_e64 s[2:3], 33, v187
	v_cndmask_b32_e64 v85, v85, v1, s[0:1]
	s_and_b64 s[0:1], s[0:1], s[4:5]
	v_cmp_gt_i32_e32 vcc, 32, v187
	v_cndmask_b32_e64 v84, v84, v1, s[0:1]
	s_and_b64 s[0:1], s[0:1], s[2:3]
	s_and_b64 vcc, s[0:1], vcc
	v_cndmask_b32_e64 v81, v81, v1, s[62:63]
	v_cndmask_b32_e64 v80, v80, v1, s[60:61]
	v_cndmask_b32_e64 v79, v79, v1, s[58:59]
	v_cndmask_b32_e64 v78, v78, v1, s[56:57]
	v_cndmask_b32_e64 v77, v77, v1, s[54:55]
	v_cndmask_b32_e64 v76, v76, v1, s[52:53]
	v_cndmask_b32_e64 v75, v75, v1, s[50:51]
	v_cndmask_b32_e64 v74, v74, v1, s[48:49]
	v_cndmask_b32_e64 v73, v73, v1, s[46:47]
	v_cndmask_b32_e64 v72, v72, v1, s[44:45]
	v_cndmask_b32_e64 v71, v71, v1, s[42:43]
	v_cndmask_b32_e64 v70, v70, v1, s[40:41]
	v_cndmask_b32_e64 v69, v69, v1, s[38:39]
	v_cndmask_b32_e64 v68, v68, v1, s[36:37]
	v_cndmask_b32_e64 v67, v67, v1, s[34:35]
	v_cndmask_b32_e64 v97, v97, v1, s[28:29]
	v_cndmask_b32_e64 v96, v96, v1, s[26:27]
	v_cndmask_b32_e64 v95, v95, v1, s[24:25]
	v_cndmask_b32_e64 v94, v94, v1, s[22:23]
	v_cndmask_b32_e64 v93, v93, v1, s[20:21]
	v_cndmask_b32_e64 v92, v92, v1, s[18:19]
	v_cndmask_b32_e64 v83, v83, v1, s[0:1]
	v_cndmask_b32_e32 v82, v82, v1, vcc
; __device__ __forceinline__ float xhalf_max(float x) { const auto r = __builtin_amdgcn_permlane32_swap(__float_as_uint(x), __float_as_uint(x), false, false); return fmaxf(__uint_as_float(r[0]), __uint_as_float(r[1])); }
; __device__ __forceinline__ float xhalf_sum(float x) { const auto r = __builtin_amdgcn_permlane32_swap(__float_as_uint(x), __float_as_uint(x), false, false); return __uint_as_float(r[0]) + __uint_as_float(r[1]); }
; template <int MODE, int NQ> ...
;     ...
;         if (MODE == M_SEL) { jn = rem ? (int)__builtin_ctzll(rem) : -1; rem &= rem - 1ull; } else { jn = (j + 1 <= jhi) ? j + 1 : -1; }
;         if (jn >= 0) stage_load<HASP, HASV>(st, Kg + (size_t)jn * 64 * ldk, ldk, Pg + (size_t)jn * 64 * 64, Vg + (size_t)jn * 64 * ldv, ldv, tid);
;     ...
;                 float mx = s0[0];
; #pragma unroll
;                 for (int r = 1; r < 16; ++r) mx = fmaxf(mx, s0[r]);
; #pragma unroll
;                 for (int r = 0; r < 16; ++r) mx = fmaxf(mx, s1[r]);
;                 mx = xhalf_max(mx);
;                 if (MODE == M_SEL) mx = lv ? mx : -__builtin_inff();
;                 const float mn = fmaxf(m, mx * C), alpha = __builtin_amdgcn_exp2f(m - mn);
;                 m = mn;
;                 float rs = 0.f;
; #pragma unroll
;                 for (int r = 0; r < 16; ++r) { s0[r] = __builtin_amdgcn_exp2f(s0[r] * C - mn); s1[r] = __builtin_amdgcn_exp2f(s1[r] * C - mn); rs += s0[r] + s1[r]; }
;                 rs = xhalf_sum(rs);
;                 if (MODE == M_SEL) rs = lv ? rs : 0.f;
;                 l = l * alpha + rs;
.LBB0_967:
	s_cmp_ge_u32 s64, s95
	s_cbranch_scc1 .Lmla_sm_plain
	s_nop 8
	s_xor_b32 s1, s65, 1
	s_mul_i32 s2, s1, 0x5000
	s_mul_i32 vcc_lo, s1, s100
	s_mul_i32 s1, s1, 0x6400
	v_max_f32_e32 v189, v67, v67
	s_add_i32 m0, s98, s1
	v_max_f32_e32 v191, v66, v66
	v_max_f32_e32 v189, v191, v189
	global_load_lds_dwordx4 v146, s[30:31]
	v_max3_f32 v189, v189, v68, v69
	v_max3_f32 v189, v189, v70, v71
	v_add_u32_e32 v146, v146, v152
	v_max3_f32 v189, v189, v72, v73
	v_max3_f32 v189, v189, v74, v75
	v_max3_f32 v189, v189, v76, v77
	v_max3_f32 v189, v189, v78, v79
	v_max3_f32 v189, v189, v80, v81
	v_max3_f32 v189, v189, v82, v83
	v_max3_f32 v189, v189, v84, v85
	v_max3_f32 v189, v189, v86, v87
	v_max3_f32 v189, v189, v88, v89
	v_max3_f32 v189, v189, v90, v91
	v_max3_f32 v189, v189, v92, v93
	v_max3_f32 v189, v189, v94, v95
	v_max3_f32 v189, v189, v96, v97
	v_mov_b32_e32 v191, v189
	s_nop 1
	s_add_i32 vcc_hi, s98, 0x2000
	s_add_i32 m0, vcc_hi, s1
	v_permlane32_swap_b32_e32 v189, v191
	v_max_f32_e32 v191, v191, v191
	global_load_lds_dwordx4 v147, s[30:31]
	v_max_f32_e32 v189, v189, v189
	v_max_f32_e32 v189, v189, v191
	v_add_u32_e32 v147, v147, v153
	v_mul_f32_e32 v189, 0x3dd53b94, v189
	v_max_f32_e32 v191, v190, v190
	v_max_f32_e32 v189, v191, v189
	v_fma_f32 v66, v66, s77, -v189
	v_exp_f32_e32 v191, v66
	v_fma_f32 v66, v82, s77, -v189
	v_exp_f32_e32 v82, v66
	v_fma_f32 v66, v67, s77, -v189
	v_exp_f32_e32 v193, v66
	v_fma_f32 v66, v83, s77, -v189
	v_fma_f32 v68, v68, s77, -v189
	v_exp_f32_e32 v67, v66
	v_exp_f32_e32 v195, v68
	v_fma_f32 v68, v84, s77, -v189
	v_exp_f32_e32 v68, v68
	s_add_i32 vcc_hi, s98, 0x4000
	s_add_i32 m0, vcc_hi, s1
	v_fma_f32 v69, v69, s77, -v189
	v_add_f32_e32 v83, v191, v82
	global_load_lds_dwordx4 v148, s[30:31]
	v_exp_f32_e32 v197, v69
	v_fma_f32 v69, v85, s77, -v189
	v_add_u32_e32 v148, v148, v154
	v_sub_f32_e32 v66, v190, v189
	v_add_f32_e32 v190, 0, v83
	v_exp_f32_e32 v83, v69
	v_add_f32_e32 v192, v193, v67
	v_fma_f32 v70, v70, s77, -v189
	v_add_f32_e32 v69, v192, v190
	v_add_f32_e32 v84, v195, v68
	v_exp_f32_e32 v190, v70
	v_fma_f32 v70, v86, s77, -v189
	v_add_f32_e32 v69, v84, v69
	v_exp_f32_e32 v84, v70
	v_fma_f32 v70, v71, s77, -v189
	v_add_f32_e32 v194, v197, v83
	v_exp_f32_e32 v192, v70
	v_fma_f32 v70, v87, s77, -v189
	s_add_i32 m0, s99, vcc_lo
	v_fma_f32 v71, v72, s77, -v189
	v_exp_f32_e32 v85, v70
	global_load_lds_dwordx4 v149, s[30:31]
	v_add_f32_e32 v69, v194, v69
	v_exp_f32_e32 v194, v71
	v_add_u32_e32 v149, v149, v155
	v_fma_f32 v71, v88, s77, -v189
	v_exp_f32_e32 v72, v71
	v_add_f32_e32 v70, v190, v84
	v_add_f32_e32 v69, v70, v69
	v_add_f32_e32 v70, v192, v85
	v_fma_f32 v71, v73, s77, -v189
	v_exp_f32_e32 v196, v71
	v_fma_f32 v71, v89, s77, -v189
	v_add_f32_e32 v69, v70, v69
	v_add_f32_e32 v70, v194, v72
	v_exp_f32_e32 v86, v71
	v_add_f32_e32 v71, v70, v69
	v_fma_f32 v69, v74, s77, -v189
	v_exp_f32_e32 v87, v69
	v_fma_f32 v69, v90, s77, -v189
	s_add_i32 vcc_hi, s98, 0xe400
	s_add_i32 m0, vcc_hi, s2
	v_exp_f32_e32 v69, v69
	v_add_f32_e32 v73, v196, v86
	global_load_lds_dwordx4 v150, s[30:31]
	v_fma_f32 v70, v75, s77, -v189
	v_add_f32_e32 v71, v73, v71
	v_add_u32_e32 v150, 0x40000, v150
	v_add_f32_e32 v73, v87, v69
	v_exp_f32_e32 v88, v70
	v_fma_f32 v70, v91, s77, -v189
	v_add_f32_e32 v73, v73, v71
	v_fma_f32 v71, v76, s77, -v189
	v_exp_f32_e32 v70, v70
	v_exp_f32_e32 v89, v71
	v_fma_f32 v71, v92, s77, -v189
	v_fma_f32 v75, v77, s77, -v189
	v_exp_f32_e32 v71, v71
	v_exp_f32_e32 v90, v75
	v_fma_f32 v75, v93, s77, -v189
	v_fma_f32 v76, v78, s77, -v189
	v_exp_f32_e32 v75, v75
	v_exp_f32_e32 v91, v76
	s_add_i32 m0, s101, s2
	v_fma_f32 v76, v94, s77, -v189
	v_fma_f32 v77, v79, s77, -v189
	global_load_lds_dwordx4 v151, s[30:31]
	v_exp_f32_e32 v76, v76
	v_exp_f32_e32 v92, v77
	v_add_u32_e32 v151, 0x40000, v151
	v_fma_f32 v77, v95, s77, -v189
	v_add_f32_e32 v74, v88, v70
	v_exp_f32_e32 v78, v77
	v_add_f32_e32 v73, v74, v73
	v_add_f32_e32 v74, v89, v71
	v_add_f32_e32 v73, v74, v73
	v_add_f32_e32 v74, v90, v75
	v_add_f32_e32 v73, v74, v73
	v_add_f32_e32 v74, v91, v76
	v_add_f32_e32 v73, v74, v73
	v_add_f32_e32 v74, v92, v78
	v_add_f32_e32 v73, v74, v73
	v_fma_f32 v74, v80, s77, -v189
	v_exp_f32_e32 v80, v74
	v_fma_f32 v74, v96, s77, -v189
	v_exp_f32_e32 v77, v74
	v_fma_f32 v74, v81, s77, -v189
	v_exp_f32_e32 v81, v74
	v_fma_f32 v74, v97, s77, -v189
	v_exp_f32_e32 v79, v74
	v_exp_f32_e32 v66, v66
	v_add_f32_e32 v74, v80, v77
	v_add_f32_e32 v73, v74, v73
	v_add_f32_e32 v74, v81, v79
	v_add_f32_e32 v73, v74, v73
	v_mov_b32_e32 v74, v73
	s_branch .Lmla_sm_join

; template <int MODE, int NQ> ...
;     ...
;                 l = l * alpha + rs;
;                 if (MODE != M_CMP1) {
;                     if (!__all(alpha == 1.0f)) {
; #pragma unroll
;                         for (int db = 0; db < 4; ++db)
; #pragma unroll
;                             for (int r = 0; r < 16; ++r) O[db][r] *= alpha;
;                     }
;                 }
.Lmla_sm_join:
	v_cmp_eq_f32_e32 vcc, 1.0, v66
	s_cmp_eq_u64 vcc, exec
	v_permlane32_swap_b32_e32 v73, v74
	s_cbranch_scc1 .LBB0_969
	v_pk_mul_f32 v[64:65], v[64:65], v[66:67] op_sel_hi:[1,0]
	v_pk_mul_f32 v[62:63], v[62:63], v[66:67] op_sel_hi:[1,0]
	v_pk_mul_f32 v[60:61], v[60:61], v[66:67] op_sel_hi:[1,0]
	v_pk_mul_f32 v[58:59], v[58:59], v[66:67] op_sel_hi:[1,0]
	v_pk_mul_f32 v[56:57], v[56:57], v[66:67] op_sel_hi:[1,0]
	v_pk_mul_f32 v[54:55], v[54:55], v[66:67] op_sel_hi:[1,0]
	v_pk_mul_f32 v[52:53], v[52:53], v[66:67] op_sel_hi:[1,0]
	v_pk_mul_f32 v[50:51], v[50:51], v[66:67] op_sel_hi:[1,0]
	v_pk_mul_f32 v[48:49], v[48:49], v[66:67] op_sel_hi:[1,0]
	v_pk_mul_f32 v[46:47], v[46:47], v[66:67] op_sel_hi:[1,0]
	v_pk_mul_f32 v[44:45], v[44:45], v[66:67] op_sel_hi:[1,0]
	v_pk_mul_f32 v[42:43], v[42:43], v[66:67] op_sel_hi:[1,0]
	v_pk_mul_f32 v[40:41], v[40:41], v[66:67] op_sel_hi:[1,0]
	v_pk_mul_f32 v[38:39], v[38:39], v[66:67] op_sel_hi:[1,0]
	v_pk_mul_f32 v[36:37], v[36:37], v[66:67] op_sel_hi:[1,0]
	v_pk_mul_f32 v[34:35], v[34:35], v[66:67] op_sel_hi:[1,0]
	v_pk_mul_f32 v[32:33], v[32:33], v[66:67] op_sel_hi:[1,0]
	v_pk_mul_f32 v[30:31], v[30:31], v[66:67] op_sel_hi:[1,0]
	v_pk_mul_f32 v[28:29], v[28:29], v[66:67] op_sel_hi:[1,0]
	v_pk_mul_f32 v[26:27], v[26:27], v[66:67] op_sel_hi:[1,0]
	v_pk_mul_f32 v[24:25], v[24:25], v[66:67] op_sel_hi:[1,0]
	v_pk_mul_f32 v[22:23], v[22:23], v[66:67] op_sel_hi:[1,0]
	v_pk_mul_f32 v[20:21], v[20:21], v[66:67] op_sel_hi:[1,0]
	v_pk_mul_f32 v[18:19], v[18:19], v[66:67] op_sel_hi:[1,0]
	v_pk_mul_f32 v[16:17], v[16:17], v[66:67] op_sel_hi:[1,0]
	v_pk_mul_f32 v[14:15], v[14:15], v[66:67] op_sel_hi:[1,0]
	v_pk_mul_f32 v[12:13], v[12:13], v[66:67] op_sel_hi:[1,0]
	v_pk_mul_f32 v[10:11], v[10:11], v[66:67] op_sel_hi:[1,0]
	v_pk_mul_f32 v[8:9], v[8:9], v[66:67] op_sel_hi:[1,0]
	v_pk_mul_f32 v[6:7], v[6:7], v[66:67] op_sel_hi:[1,0]
	v_pk_mul_f32 v[4:5], v[4:5], v[66:67] op_sel_hi:[1,0]
	v_pk_mul_f32 v[2:3], v[2:3], v[66:67] op_sel_hi:[1,0]

; template <int MODE, int NQ> ...
;     ...
;         if (MODE == M_SEL) { jn = rem ? (int)__builtin_ctzll(rem) : -1; rem &= rem - 1ull; } else { jn = (j + 1 <= jhi) ? j + 1 : -1; }
;         if (jn >= 0) stage_load<HASP, HASV>(st, Kg + (size_t)jn * 64 * ldk, ldk, Pg + (size_t)jn * 64 * 64, Vg + (size_t)jn * 64 * ldv, ldv, tid);
.LBB0_970:
	s_cmp_ge_u32 s64, s95
	s_cbranch_scc1 .Lmla_dma_skip2
	s_xor_b32 s1, s65, 1
	s_mul_i32 s2, s1, 0x5000
	s_mul_i32 vcc_lo, s1, s100
	s_mul_i32 s1, s1, 0x6400
	s_add_i32 m0, s98, s1
	s_add_i32 vcc_hi, s98, 0x2000
	global_load_lds_dwordx4 v146, s[30:31]
	s_add_i32 m0, vcc_hi, s1
	v_add_u32_e32 v146, v146, v152
	global_load_lds_dwordx4 v147, s[30:31]
	s_add_i32 vcc_hi, s98, 0x4000
	s_add_i32 m0, vcc_hi, s1
	v_add_u32_e32 v147, v147, v153
	global_load_lds_dwordx4 v148, s[30:31]
	s_add_i32 m0, s99, vcc_lo
	v_add_u32_e32 v148, v148, v154
	global_load_lds_dwordx4 v149, s[30:31]
	s_add_i32 vcc_hi, s98, 0xe400
	s_add_i32 m0, vcc_hi, s2
	v_add_u32_e32 v149, v149, v155
	global_load_lds_dwordx4 v150, s[30:31]
	s_add_i32 m0, s101, s2
	v_add_u32_e32 v150, 0x40000, v150
	global_load_lds_dwordx4 v151, s[30:31]
	v_add_u32_e32 v151, 0x40000, v151
